# v44 + final rmsnorm phase: loop-invariant final_gain loaded once before the loop; 8 serialized in-loop loads and their vmcnt(0) waits (which also waited for stores) removed
# speedup vs baseline: 1.0069x; 1.0069x over previous
.LBB0_898:
	s_or_b64 exec, exec, s[0:1]
	s_waitcnt lgkmcnt(0)
	v_mov_b32_e32 v0, v182
	s_barrier
	v_readlane_b32 s0, v252, 0
	v_ashrrev_i32_e32 v0, 5, v0
	v_and_b32_e32 v0, -2, v0
	v_lshl_add_u32 v16, s0, 4, v0
	s_movk_i32 s0, 0x4000
	v_cmp_gt_i32_e32 vcc, s0, v16
	s_and_saveexec_b64 s[0:1], vcc
	s_cbranch_execz .LBB0_901
	v_lshlrev_b32_e32 v0, 2, v182
	v_and_b32_e32 v18, 0xfc, v0
	v_mov_b32_e32 v1, 0
	v_lshlrev_b32_e32 v0, 2, v18
	v_lshl_add_u64 v[20:21], s[54:55], 0, v[0:1]
	s_mov_b64 s[0:1], 0x1000
	v_lshl_add_u64 v[22:23], v[20:21], 0, s[0:1]
	s_mov_b64 s[0:1], 0x1400
	v_lshl_add_u64 v[24:25], v[20:21], 0, s[0:1]
	s_mov_b64 s[0:1], 0x1800
	v_lshl_add_u64 v[26:27], v[20:21], 0, s[0:1]
	s_mov_b64 s[0:1], 0x1c00
	s_lshl_b32 s5, s96, 4
	v_lshl_add_u64 v[28:29], v[20:21], 0, s[0:1]
	s_mov_b64 s[2:3], 0
	s_movk_i32 s8, 0x2000
	s_movk_i32 s9, 0x1000
	s_movk_i32 s10, 0x3000
	s_mov_b32 s4, 0x3a000000
	s_mov_b32 s11, 0x800000
	s_movk_i32 s12, 0x3fff
	v_mov_b32_e32 v30, 0x358637bd
	global_load_dwordx4 v[140:143], v[20:21], off
	global_load_dwordx4 v[144:147], v[20:21], off offset:1024
	global_load_dwordx4 v[148:151], v[20:21], off offset:2048
	global_load_dwordx4 v[152:155], v[20:21], off offset:3072
	global_load_dwordx4 v[156:159], v[22:23], off
	global_load_dwordx4 v[160:163], v[24:25], off
	global_load_dwordx4 v[164:167], v[26:27], off
	global_load_dwordx4 v[168:171], v[28:29], off
	s_waitcnt vmcnt(0)
.LBB0_900:
	v_ashrrev_i32_e32 v17, 31, v16
	v_lshlrev_b64 v[0:1], 11, v[16:17]
	v_or_b32_e32 v0, v0, v18
	v_lshlrev_b64 v[32:33], 2, v[0:1]
	v_lshl_add_u64 v[2:3], v[0:1], 1, s[6:7]
	v_lshl_add_u64 v[0:1], s[52:53], 0, v[32:33]
	v_add_co_u32_e32 v4, vcc, 0x2000, v0
	s_mov_b64 s[0:1], vcc
	v_add_co_u32_e32 v6, vcc, 0x1000, v2
	global_load_dwordx2 v[58:59], v[2:3], off
	global_load_dwordx2 v[60:61], v[2:3], off offset:512
	global_load_dwordx2 v[68:69], v[2:3], off offset:1024
	v_addc_co_u32_e32 v7, vcc, 0, v3, vcc
	global_load_dwordx4 v[34:37], v[0:1], off
	global_load_dwordx4 v[38:41], v[0:1], off offset:1024
	global_load_dwordx2 v[70:71], v[6:7], off
	global_load_dwordx2 v[72:73], v[6:7], off offset:512
	v_addc_co_u32_e64 v5, vcc, 0, v1, s[0:1]
	global_load_dwordx4 v[42:45], v[4:5], off
	global_load_dwordx4 v[46:49], v[4:5], off offset:1024
	global_load_dwordx4 v[50:53], v[0:1], off offset:2048
	global_load_dwordx2 v[106:107], v[6:7], off offset:1024
	global_load_dwordx4 v[54:57], v[4:5], off offset:2048
	global_load_dwordx2 v[108:109], v[2:3], off offset:1536
	global_load_dwordx4 v[64:67], v[0:1], off offset:3072
	global_load_dwordx2 v[122:123], v[6:7], off offset:1536
	global_load_dwordx4 v[74:77], v[4:5], off offset:3072
	global_load_dwordx2 v[124:125], v[2:3], off offset:2048
	global_load_dwordx2 v[126:127], v[2:3], off offset:2560
	global_load_dwordx2 v[102:103], v[2:3], off offset:3072
	global_load_dwordx2 v[100:101], v[2:3], off offset:3584
	v_add_co_u32_e32 v62, vcc, s9, v0
	global_load_dwordx2 v[128:129], v[6:7], off offset:2048
	global_load_dwordx2 v[130:131], v[6:7], off offset:2560
	global_load_dwordx2 v[104:105], v[6:7], off offset:3072
	global_load_dwordx2 v[98:99], v[6:7], off offset:3584
	v_addc_co_u32_e32 v63, vcc, 0, v1, vcc
	v_add_co_u32_e32 v82, vcc, s10, v0
	v_add_u32_e32 v16, s5, v16
	s_nop 0
	v_addc_co_u32_e32 v83, vcc, 0, v1, vcc
	global_load_dwordx4 v[78:81], v[62:63], off
	global_load_dwordx4 v[110:113], v[62:63], off offset:1024
	global_load_dwordx4 v[12:15], v[62:63], off offset:2048
	global_load_dwordx4 v[4:7], v[62:63], off offset:3072
	global_load_dwordx4 v[114:117], v[82:83], off
	global_load_dwordx4 v[118:121], v[82:83], off offset:1024
	global_load_dwordx4 v[8:11], v[82:83], off offset:2048
	global_load_dwordx4 v[0:3], v[82:83], off offset:3072
	s_waitcnt vmcnt(0)
	v_lshlrev_b32_e32 v62, 16, v58
	v_and_b32_e32 v63, 0xffff0000, v58
	v_lshlrev_b32_e32 v58, 16, v59
	v_and_b32_e32 v59, 0xffff0000, v59
	v_lshlrev_b32_e32 v82, 16, v60
	v_and_b32_e32 v83, 0xffff0000, v60
	v_lshlrev_b32_e32 v84, 16, v61
	v_and_b32_e32 v85, 0xffff0000, v61
	v_pk_add_f32 v[60:61], v[34:35], v[62:63]
	v_pk_add_f32 v[62:63], v[36:37], v[58:59]
	v_pk_add_f32 v[34:35], v[38:39], v[82:83]
	v_pk_add_f32 v[36:37], v[40:41], v[84:85]
	v_lshlrev_b32_e32 v38, 16, v70
	v_and_b32_e32 v39, 0xffff0000, v70
	v_lshlrev_b32_e32 v40, 16, v71
	v_and_b32_e32 v41, 0xffff0000, v71
	v_lshlrev_b32_e32 v58, 16, v72
	v_and_b32_e32 v59, 0xffff0000, v72
	v_lshlrev_b32_e32 v132, 16, v68
	v_lshlrev_b32_e32 v82, 16, v73
	v_and_b32_e32 v83, 0xffff0000, v73
	v_pk_add_f32 v[70:71], v[42:43], v[38:39]
	v_pk_add_f32 v[72:73], v[44:45], v[40:41]
	v_pk_add_f32 v[40:41], v[46:47], v[58:59]
	v_and_b32_e32 v133, 0xffff0000, v68
	v_lshlrev_b32_e32 v42, 16, v69
	v_and_b32_e32 v43, 0xffff0000, v69
	v_lshlrev_b32_e32 v46, 16, v107
	v_and_b32_e32 v47, 0xffff0000, v107
	v_pk_add_f32 v[38:39], v[50:51], v[132:133]
	v_pk_add_f32 v[50:51], v[52:53], v[42:43]
	v_pk_add_f32 v[52:53], v[56:57], v[46:47]
	v_lshlrev_b32_e32 v46, 16, v108
	v_and_b32_e32 v47, 0xffff0000, v108
	v_pk_add_f32 v[46:47], v[64:65], v[46:47]
	v_pk_add_f32 v[44:45], v[48:49], v[82:83]
	v_lshlrev_b32_e32 v42, 16, v106
	v_and_b32_e32 v43, 0xffff0000, v106
	v_lshlrev_b32_e32 v48, 16, v109
	v_and_b32_e32 v49, 0xffff0000, v109
	v_mov_b32_e32 v64, v39
	v_mov_b32_e32 v65, v47
	v_pk_add_f32 v[42:43], v[54:55], v[42:43]
	v_pk_add_f32 v[54:55], v[66:67], v[48:49]
	v_mov_b32_e32 v58, v38
	v_mov_b32_e32 v59, v46
	v_pk_mul_f32 v[64:65], v[64:65], v[64:65]
	v_lshlrev_b32_e32 v48, 16, v122
	v_and_b32_e32 v49, 0xffff0000, v122
	v_pk_fma_f32 v[58:59], v[58:59], v[58:59], v[64:65]
	v_mov_b32_e32 v64, v50
	v_mov_b32_e32 v65, v54
	v_pk_add_f32 v[48:49], v[74:75], v[48:49]
	v_pk_fma_f32 v[58:59], v[64:65], v[64:65], v[58:59]
	v_mov_b32_e32 v64, v51
	v_mov_b32_e32 v65, v55
	v_lshlrev_b32_e32 v56, 16, v123
	v_and_b32_e32 v57, 0xffff0000, v123
	v_pk_fma_f32 v[108:109], v[64:65], v[64:65], v[58:59]
	v_mov_b32_e32 v64, v43
	v_mov_b32_e32 v65, v49
	v_pk_add_f32 v[56:57], v[76:77], v[56:57]
	v_mov_b32_e32 v58, v42
	v_mov_b32_e32 v59, v48
	v_pk_mul_f32 v[64:65], v[64:65], v[64:65]
	v_lshlrev_b32_e32 v68, 16, v127
	v_pk_fma_f32 v[58:59], v[58:59], v[58:59], v[64:65]
	v_mov_b32_e32 v64, v52
	v_mov_b32_e32 v65, v56
	v_pk_fma_f32 v[58:59], v[64:65], v[64:65], v[58:59]
	v_mov_b32_e32 v64, v53
	v_mov_b32_e32 v65, v57
	v_pk_fma_f32 v[106:107], v[64:65], v[64:65], v[58:59]
	v_lshlrev_b32_e32 v64, 16, v125
	v_and_b32_e32 v65, 0xffff0000, v125
	v_pk_add_f32 v[74:75], v[80:81], v[64:65]
	v_lshlrev_b32_e32 v64, 16, v128
	v_and_b32_e32 v65, 0xffff0000, v128
	v_lshlrev_b32_e32 v58, 16, v124
	v_and_b32_e32 v59, 0xffff0000, v124
	v_pk_add_f32 v[66:67], v[114:115], v[64:65]
	v_lshlrev_b32_e32 v64, 16, v129
	v_and_b32_e32 v65, 0xffff0000, v129
	v_pk_add_f32 v[58:59], v[78:79], v[58:59]
	v_pk_add_f32 v[78:79], v[116:117], v[64:65]
	v_lshlrev_b32_e32 v64, 16, v126
	v_and_b32_e32 v65, 0xffff0000, v126
	v_pk_add_f32 v[64:65], v[110:111], v[64:65]
	v_and_b32_e32 v69, 0xffff0000, v127
	v_pk_add_f32 v[76:77], v[112:113], v[68:69]
	v_mov_b32_e32 v112, v59
	v_mov_b32_e32 v113, v65
	v_lshlrev_b32_e32 v68, 16, v130
	v_and_b32_e32 v69, 0xffff0000, v130
	v_mov_b32_e32 v110, v58
	v_mov_b32_e32 v111, v64
	v_pk_mul_f32 v[112:113], v[112:113], v[112:113]
	v_pk_add_f32 v[68:69], v[118:119], v[68:69]
	v_pk_fma_f32 v[110:111], v[110:111], v[110:111], v[112:113]
	v_mov_b32_e32 v112, v74
	v_mov_b32_e32 v113, v76
	v_lshlrev_b32_e32 v80, 16, v131
	v_and_b32_e32 v81, 0xffff0000, v131
	v_pk_fma_f32 v[110:111], v[112:113], v[112:113], v[110:111]
	v_mov_b32_e32 v112, v75
	v_mov_b32_e32 v113, v77
	v_mov_b32_e32 v114, v67
	v_mov_b32_e32 v115, v69
	v_pk_add_f32 v[80:81], v[120:121], v[80:81]
	v_pk_fma_f32 v[110:111], v[112:113], v[112:113], v[110:111]
	v_mov_b32_e32 v112, v66
	v_mov_b32_e32 v113, v68
	v_pk_mul_f32 v[114:115], v[114:115], v[114:115]
	v_pk_mul_f32 v[92:93], v[60:61], v[60:61]
	v_pk_fma_f32 v[112:113], v[112:113], v[112:113], v[114:115]
	v_mov_b32_e32 v114, v78
	v_mov_b32_e32 v115, v80
	v_pk_fma_f32 v[112:113], v[114:115], v[114:115], v[112:113]
	v_mov_b32_e32 v114, v79
	v_mov_b32_e32 v115, v81
	v_pk_fma_f32 v[112:113], v[114:115], v[114:115], v[112:113]
	v_lshlrev_b32_e32 v114, 16, v102
	v_and_b32_e32 v115, 0xffff0000, v102
	v_lshlrev_b32_e32 v102, 16, v103
	v_and_b32_e32 v103, 0xffff0000, v103
	v_pk_add_f32 v[14:15], v[14:15], v[102:103]
	v_lshlrev_b32_e32 v102, 16, v104
	v_and_b32_e32 v103, 0xffff0000, v104
	v_pk_add_f32 v[8:9], v[8:9], v[102:103]
	v_lshlrev_b32_e32 v102, 16, v105
	v_and_b32_e32 v103, 0xffff0000, v105
	v_pk_add_f32 v[10:11], v[10:11], v[102:103]
	v_lshlrev_b32_e32 v102, 16, v100
	v_and_b32_e32 v103, 0xffff0000, v100
	v_lshlrev_b32_e32 v100, 16, v101
	v_and_b32_e32 v101, 0xffff0000, v101
	v_pk_add_f32 v[12:13], v[12:13], v[114:115]
	v_pk_add_f32 v[4:5], v[4:5], v[102:103]
	v_pk_add_f32 v[6:7], v[6:7], v[100:101]
	v_lshlrev_b32_e32 v100, 16, v98
	v_and_b32_e32 v101, 0xffff0000, v98
	v_pk_add_f32 v[0:1], v[0:1], v[100:101]
	v_lshlrev_b32_e32 v98, 16, v99
	v_and_b32_e32 v99, 0xffff0000, v99
	v_mov_b32_e32 v100, v13
	v_mov_b32_e32 v101, v5
	v_pk_add_f32 v[2:3], v[2:3], v[98:99]
	v_mov_b32_e32 v98, v12
	v_mov_b32_e32 v99, v4
	v_pk_mul_f32 v[100:101], v[100:101], v[100:101]
	v_pk_mul_f32 v[96:97], v[34:35], v[34:35]
	v_pk_fma_f32 v[102:103], v[98:99], v[98:99], v[100:101]
	s_nop 1
	v_mov_b64_e32 v[98:99], v[140:141]
	v_mov_b64_e32 v[100:101], v[142:143]
	v_pk_mul_f32 v[90:91], v[62:63], v[62:63]
	v_pk_mul_f32 v[94:95], v[36:37], v[36:37]
	v_add_f32_e32 v17, v96, v97
	v_add_f32_e32 v19, v92, v93
	v_add_f32_e32 v17, v94, v17
	v_add_f32_e32 v19, v90, v19
	v_add_f32_e32 v17, v95, v17
	v_add_f32_e32 v19, v91, v19
	v_pk_mul_f32 v[84:85], v[70:71], v[70:71]
	v_pk_mul_f32 v[88:89], v[40:41], v[40:41]
	v_add_f32_e32 v17, v19, v17
	v_pk_mul_f32 v[82:83], v[72:73], v[72:73]
	v_pk_mul_f32 v[86:87], v[44:45], v[44:45]
	v_add_f32_e32 v17, v17, v108
	v_add_f32_e32 v19, v88, v89
	v_add_f32_e32 v31, v84, v85
	v_mov_b32_e32 v104, v14
	v_mov_b32_e32 v105, v6
	v_add_f32_e32 v17, v17, v109
	v_add_f32_e32 v19, v86, v19
	v_add_f32_e32 v31, v82, v31
	v_pk_fma_f32 v[102:103], v[104:105], v[104:105], v[102:103]
	v_mov_b32_e32 v104, v15
	v_mov_b32_e32 v105, v7
	v_add_f32_e32 v17, v17, v110
	v_add_f32_e32 v19, v87, v19
	v_add_f32_e32 v31, v83, v31
	v_pk_fma_f32 v[102:103], v[104:105], v[104:105], v[102:103]
	v_add_f32_e32 v17, v17, v111
	v_mov_b32_e32 v92, v9
	v_mov_b32_e32 v93, v1
	v_add_f32_e32 v19, v31, v19
	v_add_f32_e32 v17, v17, v102
	v_mov_b32_e32 v90, v8
	v_mov_b32_e32 v91, v0
	v_pk_mul_f32 v[92:93], v[92:93], v[92:93]
	v_add_f32_e32 v19, v19, v106
	v_add_f32_e32 v17, v17, v103
	v_pk_fma_f32 v[90:91], v[90:91], v[90:91], v[92:93]
	v_mov_b32_e32 v92, v10
	v_mov_b32_e32 v93, v2
	v_add_f32_e32 v19, v19, v107
	v_pk_fma_f32 v[90:91], v[92:93], v[92:93], v[90:91]
	v_mov_b32_e32 v92, v11
	v_mov_b32_e32 v93, v3
	v_add_f32_e32 v19, v19, v112
	v_add_f32_dpp v17, v17, v17 quad_perm:[1,0,3,2] row_mask:0xf bank_mask:0xf bound_ctrl:1
	v_pk_fma_f32 v[90:91], v[92:93], v[92:93], v[90:91]
	v_add_f32_e32 v19, v19, v113
	v_add_f32_dpp v17, v17, v17 quad_perm:[2,3,0,1] row_mask:0xf bank_mask:0xf bound_ctrl:1
	v_add_f32_e32 v19, v19, v90
	v_add_f32_e32 v19, v19, v91
	v_add_f32_dpp v17, v17, v17 row_half_mirror row_mask:0xf bank_mask:0xf bound_ctrl:1
	v_lshl_add_u64 v[86:87], s[56:57], 0, v[32:33]
	s_nop 0
	v_add_f32_dpp v17, v17, v17 row_mirror row_mask:0xf bank_mask:0xf bound_ctrl:1
	s_nop 0
	v_readlane_b32 s1, v17, 0
	v_readlane_b32 s13, v17, 16
	v_readlane_b32 s15, v17, 32
	v_readlane_b32 s17, v17, 48
	v_add_f32_dpp v17, v19, v19 quad_perm:[1,0,3,2] row_mask:0xf bank_mask:0xf bound_ctrl:1
	v_mov_b32_e32 v83, s13
	s_nop 0
	v_add_f32_dpp v17, v17, v17 quad_perm:[2,3,0,1] row_mask:0xf bank_mask:0xf bound_ctrl:1
	s_nop 1
	v_add_f32_dpp v17, v17, v17 row_half_mirror row_mask:0xf bank_mask:0xf bound_ctrl:1
	s_nop 1
	v_add_f32_dpp v17, v17, v17 row_mirror row_mask:0xf bank_mask:0xf bound_ctrl:1
	s_nop 0
	v_readlane_b32 s18, v17, 16
	v_readlane_b32 s0, v17, 0
	v_readlane_b32 s14, v17, 32
	v_mov_b32_e32 v82, s18
	v_pk_add_f32 v[82:83], s[0:1], v[82:83]
	v_readlane_b32 s16, v17, 48
	v_pk_add_f32 v[82:83], v[82:83], s[14:15]
	s_nop 0
	v_pk_add_f32 v[82:83], v[82:83], s[16:17]
	s_nop 0
	v_pk_fma_f32 v[82:83], v[82:83], s[4:5], v[30:31] op_sel_hi:[1,0,0]
	s_nop 0
	v_mul_f32_e32 v17, 0x4b800000, v83
	v_cmp_gt_f32_e32 vcc, s11, v83
	v_mul_f32_e32 v19, 0x4b800000, v82
	v_cmp_gt_f32_e64 s[0:1], s11, v82
	v_cndmask_b32_e32 v17, v83, v17, vcc
	v_rsq_f32_e32 v17, v17
	v_cndmask_b32_e64 v19, v82, v19, s[0:1]
	v_rsq_f32_e32 v19, v19
	v_mul_f32_e32 v31, 0x45800000, v17
	v_cndmask_b32_e32 v82, v17, v31, vcc
	v_mul_f32_e32 v17, 0x45800000, v19
	v_pk_mul_f32 v[60:61], v[60:61], v[82:83] op_sel_hi:[1,0]
	v_pk_mul_f32 v[62:63], v[62:63], v[82:83] op_sel_hi:[1,0]
	v_cndmask_b32_e64 v84, v19, v17, s[0:1]
	v_pk_mul_f32 v[62:63], v[100:101], v[62:63]
	v_pk_mul_f32 v[60:61], v[98:99], v[60:61]
	global_store_dwordx4 v[86:87], v[60:63], off
	v_pk_mul_f32 v[32:33], v[70:71], v[84:85] op_sel_hi:[1,0]
	v_add_co_u32_e32 v70, vcc, s10, v86
	v_pk_mul_f32 v[60:61], v[72:73], v[84:85] op_sel_hi:[1,0]
	s_nop 0
	v_addc_co_u32_e32 v71, vcc, 0, v87, vcc
	v_pk_mul_f32 v[62:63], v[100:101], v[60:61]
	v_pk_mul_f32 v[60:61], v[98:99], v[32:33]
	global_store_dwordx4 v[70:71], v[60:63], off offset:-4096
	s_nop 1
	v_mov_b64_e32 v[60:61], v[144:145]
	v_mov_b64_e32 v[62:63], v[146:147]
	v_pk_mul_f32 v[36:37], v[36:37], v[82:83] op_sel_hi:[1,0]
	v_pk_mul_f32 v[32:33], v[34:35], v[82:83] op_sel_hi:[1,0]
	v_add_co_u32_e32 v72, vcc, s8, v86
	v_pk_mul_f32 v[14:15], v[14:15], v[82:83] op_sel_hi:[1,0]
	s_nop 0
	v_addc_co_u32_e32 v73, vcc, 0, v87, vcc
	v_pk_mul_f32 v[12:13], v[12:13], v[82:83] op_sel_hi:[1,0]
	v_pk_mul_f32 v[6:7], v[6:7], v[82:83] op_sel_hi:[1,0]
	v_pk_mul_f32 v[4:5], v[4:5], v[82:83] op_sel_hi:[1,0]
	v_pk_mul_f32 v[32:33], v[32:33], v[60:61]
	v_pk_mul_f32 v[34:35], v[36:37], v[62:63]
	global_store_dwordx4 v[86:87], v[32:35], off offset:1024
	v_pk_mul_f32 v[36:37], v[38:39], v[82:83] op_sel_hi:[1,0]
	s_nop 0
	v_pk_mul_f32 v[34:35], v[44:45], v[84:85] op_sel_hi:[1,0]
	v_pk_mul_f32 v[32:33], v[40:41], v[84:85] op_sel_hi:[1,0]
	v_pk_mul_f32 v[34:35], v[62:63], v[34:35]
	v_pk_mul_f32 v[32:33], v[60:61], v[32:33]
	global_store_dwordx4 v[72:73], v[32:35], off offset:1024
	s_nop 1
	v_mov_b64_e32 v[32:33], v[148:149]
	v_mov_b64_e32 v[34:35], v[150:151]
	v_pk_mul_f32 v[40:41], v[50:51], v[82:83] op_sel_hi:[1,0]
	v_pk_mul_f32 v[44:45], v[66:67], v[84:85] op_sel_hi:[1,0]
	v_pk_mul_f32 v[36:37], v[36:37], v[32:33]
	v_pk_mul_f32 v[38:39], v[40:41], v[34:35]
	global_store_dwordx4 v[86:87], v[36:39], off offset:2048
	v_pk_mul_f32 v[40:41], v[56:57], v[84:85] op_sel_hi:[1,0]
	s_nop 0
	v_pk_mul_f32 v[36:37], v[52:53], v[84:85] op_sel_hi:[1,0]
	v_pk_mul_f32 v[38:39], v[42:43], v[84:85] op_sel_hi:[1,0]
	v_pk_mul_f32 v[34:35], v[34:35], v[36:37]
	v_pk_mul_f32 v[32:33], v[32:33], v[38:39]
	global_store_dwordx4 v[72:73], v[32:35], off offset:2048
	s_nop 1
	v_mov_b64_e32 v[32:33], v[152:153]
	v_mov_b64_e32 v[34:35], v[154:155]
	v_pk_mul_f32 v[38:39], v[54:55], v[82:83] op_sel_hi:[1,0]
	v_pk_mul_f32 v[36:37], v[46:47], v[82:83] op_sel_hi:[1,0]
	v_pk_mul_f32 v[42:43], v[48:49], v[84:85] op_sel_hi:[1,0]
	v_pk_mul_f32 v[36:37], v[36:37], v[32:33]
	v_pk_mul_f32 v[38:39], v[38:39], v[34:35]
	v_pk_mul_f32 v[32:33], v[32:33], v[42:43]
	v_pk_mul_f32 v[34:35], v[34:35], v[40:41]
	global_store_dwordx4 v[86:87], v[36:39], off offset:3072
	global_store_dwordx4 v[72:73], v[32:35], off offset:3072
	s_nop 1
	v_mov_b64_e32 v[32:33], v[156:157]
	v_mov_b64_e32 v[34:35], v[158:159]
	v_add_co_u32_e32 v40, vcc, s9, v86
	v_pk_mul_f32 v[38:39], v[74:75], v[82:83] op_sel_hi:[1,0]
	v_pk_mul_f32 v[36:37], v[58:59], v[82:83] op_sel_hi:[1,0]
	v_addc_co_u32_e32 v41, vcc, 0, v87, vcc
	v_pk_mul_f32 v[42:43], v[78:79], v[84:85] op_sel_hi:[1,0]
	v_cmp_lt_i32_e32 vcc, s12, v16
	s_or_b64 s[2:3], vcc, s[2:3]
	v_pk_mul_f32 v[36:37], v[36:37], v[32:33]
	v_pk_mul_f32 v[38:39], v[38:39], v[34:35]
	v_pk_mul_f32 v[32:33], v[44:45], v[32:33]
	v_pk_mul_f32 v[34:35], v[42:43], v[34:35]
	global_store_dwordx4 v[40:41], v[36:39], off
	global_store_dwordx4 v[70:71], v[32:35], off
	s_nop 1
	v_mov_b64_e32 v[32:33], v[160:161]
	v_mov_b64_e32 v[34:35], v[162:163]
	v_pk_mul_f32 v[38:39], v[76:77], v[82:83] op_sel_hi:[1,0]
	v_pk_mul_f32 v[36:37], v[64:65], v[82:83] op_sel_hi:[1,0]
	v_pk_mul_f32 v[42:43], v[80:81], v[84:85] op_sel_hi:[1,0]
	v_pk_mul_f32 v[44:45], v[68:69], v[84:85] op_sel_hi:[1,0]
	v_pk_mul_f32 v[36:37], v[36:37], v[32:33]
	v_pk_mul_f32 v[38:39], v[38:39], v[34:35]
	v_pk_mul_f32 v[32:33], v[44:45], v[32:33]
	v_pk_mul_f32 v[34:35], v[42:43], v[34:35]
	global_store_dwordx4 v[40:41], v[36:39], off offset:1024
	global_store_dwordx4 v[70:71], v[32:35], off offset:1024
	s_nop 1
	v_mov_b64_e32 v[32:33], v[164:165]
	v_mov_b64_e32 v[34:35], v[166:167]
	v_pk_mul_f32 v[36:37], v[10:11], v[84:85] op_sel_hi:[1,0]
	v_pk_mul_f32 v[38:39], v[8:9], v[84:85] op_sel_hi:[1,0]
	v_pk_mul_f32 v[8:9], v[12:13], v[32:33]
	v_pk_mul_f32 v[10:11], v[14:15], v[34:35]
	v_pk_mul_f32 v[12:13], v[38:39], v[32:33]
	v_pk_mul_f32 v[14:15], v[36:37], v[34:35]
	global_store_dwordx4 v[40:41], v[8:11], off offset:2048
	global_store_dwordx4 v[70:71], v[12:15], off offset:2048
	s_nop 1
	v_mov_b64_e32 v[8:9], v[168:169]
	v_mov_b64_e32 v[10:11], v[170:171]
	s_nop 0
	v_pk_mul_f32 v[12:13], v[2:3], v[84:85] op_sel_hi:[1,0]
	v_pk_mul_f32 v[14:15], v[0:1], v[84:85] op_sel_hi:[1,0]
	v_pk_mul_f32 v[0:1], v[4:5], v[8:9]
	v_pk_mul_f32 v[2:3], v[6:7], v[10:11]
	v_pk_mul_f32 v[4:5], v[14:15], v[8:9]
	v_pk_mul_f32 v[6:7], v[12:13], v[10:11]
	global_store_dwordx4 v[40:41], v[0:3], off offset:3072
	global_store_dwordx4 v[70:71], v[4:7], off offset:3072
	s_andn2_b64 exec, exec, s[2:3]
	s_cbranch_execnz .LBB0_900
